# v10: v8 + per-XCD unit-order skew in attention A (XCDs 4-7 run sample units first)
# speedup vs baseline: 1.0034x; 1.0034x over previous
; #define SGPRF(x) __builtin_bit_cast(float, __builtin_amdgcn_readfirstlane(__builtin_bit_cast(int, (float)(x))))
; __global__ void __launch_bounds__(NTHREADS, 2) hymba_fwd(Args args) {
;     ...
;             const float lam = SGPRF(misc[0]), oscale = SGPRF(misc[1]), mshA = SGPRF(misc[2]), mshB = SGPRF(misc[3]), mshC = SGPRF(misc[4]);
;             att::UnitArgs U;
;             U.subg = ap_->in[I_SUBG] + l * 128; U.lam = lam; U.oscale = oscale; U.tile0 = 0; U.R = 0;
;             for (int u = vcu; u < 2560; u += G) {
;                 int h, qblk, S_; size_t row0;
;                 if (u < 2048) { const int b = (u & 255) >> 5, c = u & 31, i = u >> 8; h = i >> 1; qblk = (i & 1) * 32 + c; row0 = (size_t)b * SP; S_ = SP; }
;                 else { const int v = u - 2048, b = (v & 255) >> 5, c = v & 31, idx = (v >> 8) * 32 + c; h = idx >> 4; qblk = idx & 15; row0 = (size_t)MP + (size_t)b * SS; S_ = SS; }
;                 U.q0 = 128 * qblk; U.h = h; U.NT = S_ / 64; U.ldk = NZ; U.mshift = mshA;
;                 U.Qb = Z + (row0 + U.q0) * NZ + 128 * h; U.Kb = Z + row0 * NZ + 512 + 128 * h; U.Vb = Z + row0 * NZ + 1024 + 128 * h; U.Ob = MIX + (row0 + U.q0) * DM + 128 * h;
;                 U.farL = SGPRF(lutA[h * att::LUTA_STRIDE + 0]); U.farR = SGPRF(lutA[h * att::LUTA_STRIDE + 640]);
;                 att::attn_unit<0>(U, (char*)lds, wave); }
.LBB0_305:
	s_waitcnt lgkmcnt(0)
	s_add_u32 s37, s16, 0xf400000
	s_addc_u32 s38, s17, 0
	s_add_u32 s39, s16, 0x28400000
	v_writelane_b32 v255, s16, 7
	s_addc_u32 s40, s17, 0
	s_add_i32 s90, 0, 0x1c000
	v_readlane_b32 s0, v254, 51
	v_mov_b32_e32 v0, s90
	s_nop 0
	v_mov_b32_e32 v4, s0
	s_barrier
	ds_read_b128 v[0:3], v0
	ds_read_b32 v4, v4
	v_readlane_b32 s0, v254, 10
	v_readlane_b32 s1, v254, 11
	v_writelane_b32 v255, s17, 8
	s_andn2_b64 vcc, exec, s[0:1]
	s_waitcnt lgkmcnt(0)
	v_readfirstlane_b32 s0, v4
	v_readfirstlane_b32 s11, v0
	v_readfirstlane_b32 s12, v1
	v_readfirstlane_b32 s13, v2
	v_readfirstlane_b32 s10, v3
	v_writelane_b32 v255, s0, 9
	s_cbranch_vccnz .LBB0_345
	s_load_dwordx2 s[0:1], s[2:3], 0x60
	v_readlane_b32 s2, v255, 4
	v_readlane_b32 s3, v255, 5
	s_lshl_b32 s84, s2, 7
	s_lshl_b64 s[2:3], s[84:85], 2
	s_waitcnt lgkmcnt(0)
	s_add_u32 s4, s0, s2
	s_addc_u32 s5, s1, s3
	v_readlane_b32 s0, v255, 7
	v_readlane_b32 s1, v255, 8
	s_add_u32 s14, s0, 0xf4a0400
	s_addc_u32 s15, s1, 0
	v_readlane_b32 s16, v254, 2
	s_mov_b32 s41, 10
	s_cmp_ge_u32 s16, 0x80
	s_cselect_b32 s44, 0x800, 0
	s_cmp_eq_u32 s80, 0x100
	s_cselect_b32 s44, s44, 0
	s_add_i32 s16, s16, s44
	s_branch .LBB0_308
.LBB0_307:
	s_setprio 0
	s_add_i32 s16, s16, s80
	s_cmp_eq_u32 s44, 0
	s_cbranch_scc1 .Lskew_plain
	s_cmpk_gt_i32 s16, 0x9ff
	s_cselect_b32 s45, 0xa00, 0
	s_sub_i32 s16, s16, s45
	s_sub_i32 s41, s41, 1
	s_cmp_eq_u32 s41, 0
	s_branch .Lskew_join
.Lskew_plain:
	s_cmpk_gt_i32 s16, 0x9ff
.Lskew_join:
	s_waitcnt vmcnt(63) expcnt(7) lgkmcnt(15)
	s_barrier
	s_cbranch_scc1 .LBB0_345
